# gate/branch phase: static s_setprio 1 for the trailing wave group of its GEMM loops (reset at the sigmoid and mix epilogues), on top of the leading-group raise in the 256x256 GEMM phases
# speedup vs baseline: 1.0042x; 1.0005x over previous
; template <bool WIDE>
; DEVI void gemm8s(f32x4 (&acc)[4][4], const GUnit& cur, const GUnit& nxt, bool has_next, bool first, GRing& rg, bfu* lds,
;                    bool clean = false) {
;     ...
;   if (grp == 0) {
; #pragma unroll 1
;   for (int kt = 0; kt < nkt; ++kt) {
;     if (kt == 0 && !first && !clean) asm volatile("s_waitcnt vmcnt(0)" ::: "memory");
;     else asm volatile("s_waitcnt vmcnt(6)" ::: "memory");
;     RAW_BARRIER();
;     const bool own = (kt + 2 < nkt);
;     const bool fromn = !own && has_next;
;     const int tk = own ? kt + 2 : (fromn ? kt + 2 - nkt : nkt - 1);
;     const char* Ai = fromn ? Acn : Acc;
;     const char* Bi = fromn ? Bcn : Bcc;
;     const size_t sAi = fromn ? sAn : sAc, sBi = fromn ? sBn : sBc;
;     const int ldai_ = fromn ? nxt.lda : cur.lda, ldbi_ = fromn ? nxt.ldb : cur.ldb;
;     const unsigned vAi = (unsigned)((rr * ldai_ + lc8) * 2), vBi = (unsigned)((rr * ldbi_ + lc8) * 2);
;     const bfu* Ab = (const bfu*)((const char*)lds + st * STGB);
;     const bfu* Bb = Ab + 256 * 64;
;     bf16x8 tf[2][4], wf[2][4];
; #pragma unroll
;     for (int ks = 0; ks < 2; ++ks) {
; #pragma unroll
;       for (int mi = 0; mi < 4; ++mi) tf[ks][mi] = *(const bf16x8*)(Ab + (wm * 64 + mi * 16 + fr) * 64 + (((ks * 4 + fq) ^ rsw) * 8));
; #pragma unroll
;       for (int ni = 0; ni < 4; ++ni) wf[ks][ni] = *(const bf16x8*)(Bb + (wn * 64 + ni * 16 + fr) * 64 + (((ks * 4 + fq) ^ rsw) * 8));
;     }
;     ISSUE(Ai, Bi, sAi, sBi, vAi, vBi, tk, st2);
; #pragma unroll
;     for (int ks = 0; ks < 2; ++ks)
; #pragma unroll
;       for (int ni = 0; ni < 4; ++ni)
; #pragma unroll
;         for (int mi = 0; mi < 4; ++mi)
;           acc[ni][mi] = __builtin_amdgcn_mfma_f32_16x16x32_bf16(wf[ks][ni], tf[ks][mi], acc[ni][mi], 0, 0, 0);
;     if constexpr (WIDE) {
;       __builtin_amdgcn_sched_group_barrier(0x100, 8, 0);
; #pragma unroll
;       for (int i = 0; i < 6; ++i) {
;         __builtin_amdgcn_sched_group_barrier(0x008, 2, 0);
;         __builtin_amdgcn_sched_group_barrier(0x020, 1, 0);
;       }
; #pragma unroll
;       for (int i = 0; i < 4; ++i) {
;         __builtin_amdgcn_sched_group_barrier(0x008, 1, 0);
;         __builtin_amdgcn_sched_group_barrier(0x100, 2, 0);
;       }
;       __builtin_amdgcn_sched_group_barrier(0x008, 16, 0);
;     }
;     st = (st == 2) ? 0 : st + 1;
;     st2 = (st2 == 2) ? 0 : st2 + 1;
;   }
.LBB0_423:
	s_setprio 1
	s_cmp_gt_u32 s20, 13
	s_cselect_b64 s[36:37], -1, 0
	s_and_b64 s[74:75], s[36:37], exec
	s_mul_i32 s75, s66, 0xc000
	s_cselect_b32 s23, s69, s43
	s_cselect_b32 s73, s68, s42
	s_cselect_b32 s74, s10, 0x440
	s_addk_i32 s75, 0xc20
	v_add_u32_e32 v70, s75, v103
	v_add3_u32 v90, v70, v102, v101
	s_waitcnt lgkmcnt(0)
	s_barrier
	ds_read_b128 v[66:69], v90 offset:32768
	v_add3_u32 v86, v70, v100, v101
	ds_read_b128 v[70:73], v86
	ds_read_b128 v[74:77], v86 offset:2048
	ds_read_b128 v[78:81], v90 offset:34816
	ds_read_b128 v[82:85], v86 offset:4096
	ds_read_b128 v[86:89], v86 offset:6144
	s_waitcnt lgkmcnt(0)
	v_mfma_f32_16x16x32_bf16 v[62:65], v[66:69], v[70:73], v[62:65]
	v_mfma_f32_16x16x32_bf16 v[58:61], v[66:69], v[74:77], v[58:61]
	v_mfma_f32_16x16x32_bf16 v[54:57], v[66:69], v[82:85], v[54:57]
	v_mfma_f32_16x16x32_bf16 v[50:53], v[66:69], v[86:89], v[50:53]
	v_mfma_f32_16x16x32_bf16 v[46:49], v[78:81], v[70:73], v[46:49]
	v_mfma_f32_16x16x32_bf16 v[42:45], v[78:81], v[74:77], v[42:45]
	v_mfma_f32_16x16x32_bf16 v[38:41], v[78:81], v[82:85], v[38:41]
	v_mfma_f32_16x16x32_bf16 v[34:37], v[78:81], v[86:89], v[34:37]
	ds_read_b128 v[66:69], v90 offset:36864
	ds_read_b128 v[78:81], v90 offset:38912
	s_waitcnt lgkmcnt(0)
	v_mfma_f32_16x16x32_bf16 v[30:33], v[66:69], v[70:73], v[30:33]
	v_mfma_f32_16x16x32_bf16 v[26:29], v[66:69], v[74:77], v[26:29]
	v_mfma_f32_16x16x32_bf16 v[22:25], v[66:69], v[82:85], v[22:25]
	v_mfma_f32_16x16x32_bf16 v[18:21], v[66:69], v[86:89], v[18:21]
	v_mul_lo_u32 v66, s74, v98
	v_or_b32_e32 v105, v66, v99
	v_add_u32_e32 v66, s75, v104
	v_add3_u32 v94, v66, v102, v101
	v_add3_u32 v90, v66, v100, v101
	ds_read_b128 v[66:69], v94 offset:32768
	s_and_b64 s[74:75], s[36:37], exec
	s_cselect_b32 s74, -14, 2
	s_add_i32 s74, s74, s20
	v_mfma_f32_16x16x32_bf16 v[14:17], v[78:81], v[70:73], v[14:17]
	s_and_b64 s[36:37], s[36:37], exec
	s_cselect_b32 s76, s71, s39
	s_cselect_b32 s77, s70, s38
	v_mfma_f32_16x16x32_bf16 v[10:13], v[78:81], v[74:77], v[10:13]
	s_cselect_b32 s78, 0xa000, s12
	s_mul_i32 s36, s28, 0xc000
	s_ashr_i32 s75, s74, 31
	v_mfma_f32_16x16x32_bf16 v[2:5], v[78:81], v[82:85], v[2:5]
	ds_read_b128 v[70:73], v90
	ds_read_b128 v[74:77], v90 offset:2048
	ds_read_b128 v[82:85], v90 offset:4096
	ds_read_b128 v[90:93], v90 offset:6144
	s_add_i32 s79, s72, s36
	s_lshl_b64 s[36:37], s[74:75], 7
	s_add_u32 s74, s73, s36
	s_addc_u32 s75, s23, s37
	s_waitcnt lgkmcnt(0)
	v_mfma_f32_16x16x32_bf16 v[62:65], v[66:69], v[70:73], v[62:65]
	s_mov_b32 m0, s79
	v_lshlrev_b32_e32 v105, 1, v105
	v_mfma_f32_16x16x32_bf16 v[58:61], v[66:69], v[74:77], v[58:61]
	v_mfma_f32_16x16x32_bf16 v[54:57], v[66:69], v[82:85], v[54:57]
	v_mfma_f32_16x16x32_bf16 v[50:53], v[66:69], v[90:93], v[50:53]
	v_lshl_add_u64 v[66:67], s[74:75], 0, v[0:1]
	v_lshl_add_u64 v[68:69], v[66:67], 0, s[14:15]
	v_mfma_f32_16x16x32_bf16 v[6:9], v[78:81], v[86:89], v[6:9]
	ds_read_b128 v[78:81], v94 offset:34816
	ds_read_b128 v[86:89], v94 offset:36864
	ds_read_b128 v[94:97], v94 offset:38912
	global_load_lds_dwordx4 v[66:67], off
	s_add_i32 m0, s79, 0x2000
	s_waitcnt lgkmcnt(0)
	v_mfma_f32_16x16x32_bf16 v[46:49], v[78:81], v[70:73], v[46:49]
	global_load_lds_dwordx4 v[68:69], off
	v_lshl_add_u64 v[68:69], v[66:67], 0, s[8:9]
	s_add_i32 m0, s79, 0x4000
	v_lshl_add_u64 v[66:67], v[66:67], 0, s[34:35]
	global_load_lds_dwordx4 v[68:69], off
	s_add_i32 m0, s79, 0x6000
	s_add_u32 s74, s77, s36
	global_load_lds_dwordx4 v[66:67], off
	s_addc_u32 s75, s76, s37
	s_add_i32 m0, s79, 0x8000
	s_add_u32 s23, s77, s78
	s_addc_u32 s73, s76, 0
	s_add_u32 s36, s23, s36
	global_load_lds_dwordx4 v105, s[74:75]
	s_addc_u32 s37, s73, s37
	s_add_i32 m0, s79, 0xa000
	s_add_i32 s23, s66, 1
	global_load_lds_dwordx4 v105, s[36:37]
	s_cmp_lg_u32 s66, 2
	v_mfma_f32_16x16x32_bf16 v[42:45], v[78:81], v[74:77], v[42:45]
	s_cselect_b32 s66, s23, 0
	s_add_i32 s23, s28, 1
	s_cmp_lg_u32 s28, 2
	v_mfma_f32_16x16x32_bf16 v[38:41], v[78:81], v[82:85], v[38:41]
	s_cselect_b32 s28, s23, 0
	s_add_i32 s20, s20, 1
	s_cmp_eq_u32 s20, 16
	v_mfma_f32_16x16x32_bf16 v[34:37], v[78:81], v[90:93], v[34:37]
	v_mfma_f32_16x16x32_bf16 v[30:33], v[86:89], v[70:73], v[30:33]
	v_mfma_f32_16x16x32_bf16 v[26:29], v[86:89], v[74:77], v[26:29]
	v_mfma_f32_16x16x32_bf16 v[22:25], v[86:89], v[82:85], v[22:25]
	v_mfma_f32_16x16x32_bf16 v[18:21], v[86:89], v[90:93], v[18:21]
	v_mfma_f32_16x16x32_bf16 v[14:17], v[94:97], v[70:73], v[14:17]
	v_mfma_f32_16x16x32_bf16 v[10:13], v[94:97], v[74:77], v[10:13]
	v_mfma_f32_16x16x32_bf16 v[2:5], v[94:97], v[82:85], v[2:5]
	v_mfma_f32_16x16x32_bf16 v[6:9], v[94:97], v[90:93], v[6:9]
	s_cbranch_scc1 .LBB0_428

; DEVI int get_tid512() { int t = threadIdx.x; asm volatile("" : "+v"(t)); return t; }
; template <bool WIDE>
; DEVI void gemm8s(f32x4 (&acc)[4][4], const GUnit& cur, const GUnit& nxt, bool has_next, bool first, GRing& rg, bfu* lds,
;                    bool clean = false) {
;     ...
;   const int tid = get_tid512(), lane = tid & 63, wid = tid >> 6, wm = wid >> 1, wn = wid & 1;
;   const int fr = lane & 15, fq = lane >> 4;
;   const int rsw = fr >> 1;
;   const int lc = (tid & 7) ^ ((tid >> 4) & 7);
;   const int rr = tid >> 3;
;   const int lc8 = lc * 8;
;   char* lbase = (char*)lds + __builtin_amdgcn_readfirstlane(wid) * 1024;
;   const int nkt = cur.nkt;
;     ...
;   const char* Acc = (const char*)cur.A;
;   const char* Bcc = (const char*)cur.B;
;   const size_t sAc = (size_t)64 * cur.lda * 2, sBc = (size_t)64 * cur.ldb * 2;
;   const char* Acn = (const char*)nxt.A;
;   const char* Bcn = (const char*)nxt.B;
;   const size_t sAn = (size_t)64 * nxt.lda * 2, sBn = (size_t)64 * nxt.ldb * 2;
;   if (first) {
;     asm volatile("s_waitcnt vmcnt(0)" ::: "memory");
;     const unsigned v0A = (unsigned)((rr * cur.lda + lc8) * 2), v0B = (unsigned)((rr * cur.ldb + lc8) * 2);
;     ISSUE(Acc, Bcc, sAc, sBc, v0A, v0B, 0, rg.st);
;     ISSUE(Acc, Bcc, sAc, sBc, v0A, v0B, 1, (rg.st == 2) ? 0 : rg.st + 1);
;   }
;   int st = rg.st, st2 = rg.st2;
;   const int grp = WIDE ? 0 : __builtin_amdgcn_readfirstlane(wid >> 2);
;   if (grp == 0) {
; DEVI void phase4(const Params& p, int l, char* lds, float* p4s) {
;     ...
;       const GUnit ug{xn + (long)m0 * LDX, wg + ((long)bb * 1024 + n0) * LDX, LDX, LDX, 16};
;       const GUnit up{y + (long)m0 * LDX + bb * 256, wb + ((long)bb * 1024 + n0) * LDBR, LDX, LDBR, 4};
;       const int m0n = (bb < 3) ? m0 : mt2 * 256, n0n = (bb < 3) ? n0 : nt2 * 128, bbn = (bb < 3) ? bb + 1 : 0;
;       const GUnit un{xn + (long)m0n * LDX, wg + ((long)bbn * 1024 + n0n) * LDX, LDX, LDX, 16};
;       zero_acc<4>(acc);
;       gemm8s<false>(acc, ug, up, true, it == 0 && bb == 0, rg, (bfu*)lds, bb > 0);
; #pragma unroll
;       for (int ni = 0; ni < 4; ++ni) {
;         const float4 bv = *(const float4*)(p4s + bb * 128 + wn * 64 + ni * 16 + fq * 4);
; #pragma unroll
;         for (int mi = 0; mi < 4; ++mi) {
;           const float rsm = p4s[512 + wm * 64 + mi * 16 + fr];
.LBB0_429:
	s_setprio 0
	s_add_i32 s72, s67, 1
	s_lshl_b32 s28, s72, 10
	s_cmp_lg_u32 s67, 3
	s_cselect_b64 s[36:37], -1, 0
	s_and_b64 s[38:39], s[36:37], exec
	s_cselect_b32 s38, s61, s64
	s_mul_hi_u32 s56, s38, 0x880
	s_mulk_i32 s38, 0x880
	s_cselect_b32 s39, s60, s65
	s_cselect_b32 s28, s28, 0
	s_add_u32 s73, s2, s38
	s_addc_u32 s74, s3, s56
	s_ashr_i32 s38, s39, 31
	v_add_u32_e32 v66, 0x800, v181
	s_add_u32 s28, s28, s39
	v_lshl_or_b32 v0, s67, 9, v179
	ds_read2_b32 v[218:219], v66 offset1:16
	ds_read2_b32 v[216:217], v66 offset0:32 offset1:48
	ds_read_b128 v[78:81], v0
	ds_read_b128 v[74:77], v0 offset:64
	ds_read_b128 v[70:73], v0 offset:128
	ds_read_b128 v[66:69], v0 offset:192
	s_addc_u32 s38, 0, s38
	s_mulk_i32 s38, 0x880
	s_mul_hi_u32 s39, s28, 0x880
	v_mov_b32_e32 v0, v220
	s_add_i32 s39, s39, s38
	s_mulk_i32 s28, 0x880
	s_add_u32 s75, s33, s28
	v_ashrrev_i32_e32 v82, 6, v0
	v_lshrrev_b32_e32 v86, 4, v0
	v_xor_b32_e32 v86, v86, v0
	v_readfirstlane_b32 s28, v82
	s_addc_u32 s76, s22, s39
	v_ashrrev_i32_e32 v235, 3, v0
	v_lshlrev_b32_e32 v86, 3, v86
	s_lshl_b32 s28, s28, 10
	v_ashrrev_i32_e32 v83, 7, v0
	v_and_b32_e32 v85, 15, v0
	v_bfe_u32 v87, v0, 4, 2
	v_bfe_u32 v88, v0, 1, 3
	v_and_b32_e32 v236, 56, v86
	s_add_i32 s77, s28, 0xc20
	v_readfirstlane_b32 s28, v0
	v_mul_lo_u32 v0, v235, s83
	s_or_b64 s[38:39], s[40:41], s[36:37]
	v_and_b32_e32 v84, 1, v82
	v_or_b32_e32 v0, v236, v0
	v_xor_b32_e32 v82, v87, v88
	v_bitop3_b32 v86, v87, v88, 4 bitop3:0x36
	s_mov_b64 s[36:37], -1
	s_cmpk_gt_u32 s28, 0xff
	v_lshlrev_b32_e32 v0, 1, v0
	v_lshlrev_b32_e32 v237, 13, v83
	v_lshlrev_b32_e32 v238, 7, v85
	v_lshlrev_b32_e32 v239, 13, v84
	v_lshlrev_b32_e32 v240, 4, v82
	v_lshlrev_b32_e32 v241, 4, v86
	s_cbranch_scc1 .LBB0_467
	s_and_b64 vcc, exec, s[36:37]
	s_cbranch_vccnz .LBB0_470

; DEVI float lo2f(unsigned u) { return __uint_as_float(u << 16); }
; DEVI float hi2f(unsigned u) { return __uint_as_float(u & 0xffff0000u); }
; DEVI float sigmoidf_(float x) { return __builtin_amdgcn_rcpf(1.f + __expf(-x)); }
; DEVI void phase4(const Params& p, int l, char* lds, float* p4s) {
;     ...
; #pragma unroll
;       for (int ni = 0; ni < 4; ++ni) {
;         const float4 bv = *(const float4*)(p4s + bb * 128 + wn * 64 + ni * 16 + fq * 4);
; #pragma unroll
;         for (int mi = 0; mi < 4; ++mi) {
;           const float rsm = p4s[512 + wm * 64 + mi * 16 + fr];
;           gp[ni][mi].x = pack2(sigmoidf_(acc[ni][mi][0] * rsm + bv.x), sigmoidf_(acc[ni][mi][1] * rsm + bv.y));
;           gp[ni][mi].y = pack2(sigmoidf_(acc[ni][mi][2] * rsm + bv.z), sigmoidf_(acc[ni][mi][3] * rsm + bv.w));
;         }
;       }
;       zero_acc<4>(acc);
;       gemm8s<false>(acc, up, un, (bb < 3) || have2, false, rg, (bfu*)lds, true);
; #pragma unroll
;       for (int ni = 0; ni < 4; ++ni)
; #pragma unroll
;         for (int mi = 0; mi < 4; ++mi) {
;           float v0 = lo2f(gp[ni][mi].x) * acc[ni][mi][0];
;           float v1 = hi2f(gp[ni][mi].x) * acc[ni][mi][1];
;           float v2 = lo2f(gp[ni][mi].y) * acc[ni][mi][2];
;           float v3 = hi2f(gp[ni][mi].y) * acc[ni][mi][3];
;           if (bb > 0) {
;             v0 += lo2f(mixp[ni][mi].x); v1 += hi2f(mixp[ni][mi].x);
;             v2 += lo2f(mixp[ni][mi].y); v3 += hi2f(mixp[ni][mi].y);
;           }
;           mixp[ni][mi].x = pack2(v0, v1);
;           mixp[ni][mi].y = pack2(v2, v3);
;         }
.LBB0_433:
	s_setprio 0
	s_waitcnt lgkmcnt(0)
	v_fma_f32 v0, v62, v218, v78
	v_fma_f32 v62, v63, v218, v79
	v_fma_f32 v63, v64, v218, v80
	v_fma_f32 v64, v65, v218, v81
	v_mul_f32_e32 v0, 0xbfb8aa3b, v0
	v_mul_f32_e32 v62, 0xbfb8aa3b, v62
	v_mul_f32_e32 v63, 0xbfb8aa3b, v63
	v_mul_f32_e32 v64, 0xbfb8aa3b, v64
	v_exp_f32_e32 v0, v0
	v_exp_f32_e32 v62, v62
	v_exp_f32_e32 v63, v63
	v_exp_f32_e32 v64, v64
	v_add_f32_e32 v0, 1.0, v0
	v_add_f32_e32 v62, 1.0, v62
	v_add_f32_e32 v63, 1.0, v63
	v_add_f32_e32 v64, 1.0, v64
	v_rcp_f32_e32 v0, v0
	v_rcp_f32_e32 v62, v62
	v_rcp_f32_e32 v63, v63
	v_rcp_f32_e32 v64, v64
	s_cmp_lg_u32 s67, 0
	v_cvt_pk_bf16_f32 v0, v0, v62
	v_lshlrev_b32_e32 v62, 16, v0
	v_cvt_pk_bf16_f32 v65, v63, v64
	v_and_b32_e32 v63, 0xffff0000, v0
	v_lshlrev_b32_e32 v64, 16, v65
	v_and_b32_e32 v65, 0xffff0000, v65
	s_cselect_b64 s[36:37], -1, 0
	s_cmp_eq_u32 s67, 0
	v_pk_mul_f32 v[62:63], v[158:159], v[62:63]
	v_pk_mul_f32 v[64:65], v[160:161], v[64:65]
	s_cbranch_scc1 .LBB0_435
	v_lshlrev_b32_e32 v138, 16, v214
	v_and_b32_e32 v139, 0xffff0000, v214
	v_pk_add_f32 v[62:63], v[62:63], v[138:139]
	v_lshlrev_b32_e32 v138, 16, v215
	v_and_b32_e32 v139, 0xffff0000, v215
	v_pk_add_f32 v[64:65], v[64:65], v[138:139]

; #define RAW_BARRIER() do { asm volatile("s_waitcnt lgkmcnt(0)" ::: "memory"); __builtin_amdgcn_s_barrier(); } while (0)
; template <bool WIDE>
; DEVI void gemm8s(f32x4 (&acc)[4][4], const GUnit& cur, const GUnit& nxt, bool has_next, bool first, GRing& rg, bfu* lds,
;                    bool clean = false) {
;     ...
;   for (int kt = 0; kt < nkt; ++kt) {
;     if (kt == 0 && !first && !clean) asm volatile("s_waitcnt vmcnt(0)" ::: "memory");
;     else asm volatile("s_waitcnt vmcnt(6)" ::: "memory");
;     RAW_BARRIER();
;     const bool own = (kt + 2 < nkt);
;     const bool fromn = !own && has_next;
;     const int tk = own ? kt + 2 : (fromn ? kt + 2 - nkt : nkt - 1);
;     const char* Ai = fromn ? Acn : Acc;
;     const char* Bi = fromn ? Bcn : Bcc;
;     const size_t sAi = fromn ? sAn : sAc, sBi = fromn ? sBn : sBc;
;     const int ldai_ = fromn ? nxt.lda : cur.lda, ldbi_ = fromn ? nxt.ldb : cur.ldb;
;     const unsigned vAi = (unsigned)((rr * ldai_ + lc8) * 2), vBi = (unsigned)((rr * ldbi_ + lc8) * 2);
;     const bfu* Ab = (const bfu*)((const char*)lds + st * STGB);
;     const bfu* Bb = Ab + 256 * 64;
;     bf16x8 tf[2][4], wf[2][4];
; #pragma unroll
;     for (int ks = 0; ks < 2; ++ks) {
; #pragma unroll
;       for (int mi = 0; mi < 4; ++mi) tf[ks][mi] = *(const bf16x8*)(Ab + (wm * 64 + mi * 16 + fr) * 64 + (((ks * 4 + fq) ^ rsw) * 8));
; #pragma unroll
;       for (int ni = 0; ni < 4; ++ni) wf[ks][ni] = *(const bf16x8*)(Bb + (wn * 64 + ni * 16 + fr) * 64 + (((ks * 4 + fq) ^ rsw) * 8));
;     }
;     ISSUE(Ai, Bi, sAi, sBi, vAi, vBi, tk, st2);
; #pragma unroll
;     for (int ks = 0; ks < 2; ++ks)
; #pragma unroll
;       for (int ni = 0; ni < 4; ++ni)
; #pragma unroll
;         for (int mi = 0; mi < 4; ++mi)
;           acc[ni][mi] = __builtin_amdgcn_mfma_f32_16x16x32_bf16(wf[ks][ni], tf[ks][mi], acc[ni][mi], 0, 0, 0);
.LBB0_471:
	s_setprio 1
	s_cmp_gt_u32 s28, 1
	s_cselect_b64 s[36:37], -1, 0
	s_add_i32 s78, s28, -2
	s_and_b64 s[56:57], s[38:39], s[36:37]
	s_and_b64 s[36:37], s[56:57], exec
	s_cselect_b32 s78, s78, 3
	s_add_i32 s79, s28, 2
	s_cmp_gt_u32 s28, 1
	s_cselect_b64 s[36:37], -1, 0
	s_and_b64 s[36:37], s[36:37], exec
	s_mul_i32 s66, s20, 0xc000
	s_cselect_b32 s36, s78, s79
	s_and_b64 s[78:79], s[56:57], exec
	s_cselect_b32 s78, s74, s69
	s_cselect_b32 s79, s73, s68
	s_cselect_b32 s37, 0x440, s10
	s_addk_i32 s66, 0xc20
	v_add_u32_e32 v138, s66, v240
	s_waitcnt vmcnt(6)
	v_add3_u32 v166, v138, v237, v238
	v_add3_u32 v170, v138, v239, v238
	s_waitcnt lgkmcnt(0)
	s_barrier
	ds_read_b128 v[138:141], v170 offset:32768
	ds_read_b128 v[146:149], v166
	ds_read_b128 v[150:153], v166 offset:2048
	ds_read_b128 v[154:157], v170 offset:34816
	ds_read_b128 v[162:165], v166 offset:4096
	ds_read_b128 v[166:169], v166 offset:6144
	s_waitcnt lgkmcnt(0)
	v_mfma_f32_16x16x32_bf16 v[158:161], v[138:141], v[146:149], v[158:161]
	s_and_b64 s[56:57], s[56:57], exec
	s_mul_i32 s80, s23, 0xc000
	s_cselect_b32 s81, s75, s70
	v_mfma_f32_16x16x32_bf16 v[142:145], v[138:141], v[150:153], v[142:145]
	s_cselect_b32 s82, s12, 0xa000
	v_mfma_f32_16x16x32_bf16 v[134:137], v[138:141], v[162:165], v[134:137]
	v_mfma_f32_16x16x32_bf16 v[130:133], v[138:141], v[166:169], v[130:133]
	v_mfma_f32_16x16x32_bf16 v[126:129], v[154:157], v[146:149], v[126:129]
	v_mfma_f32_16x16x32_bf16 v[122:125], v[154:157], v[150:153], v[122:125]
	v_mfma_f32_16x16x32_bf16 v[118:121], v[154:157], v[162:165], v[118:121]
	v_mfma_f32_16x16x32_bf16 v[114:117], v[154:157], v[166:169], v[114:117]
	ds_read_b128 v[138:141], v170 offset:36864
	ds_read_b128 v[154:157], v170 offset:38912
	s_waitcnt lgkmcnt(0)
	v_mfma_f32_16x16x32_bf16 v[110:113], v[138:141], v[146:149], v[110:113]
	v_mfma_f32_16x16x32_bf16 v[106:109], v[138:141], v[150:153], v[106:109]
	v_mfma_f32_16x16x32_bf16 v[102:105], v[138:141], v[162:165], v[102:105]
	v_mfma_f32_16x16x32_bf16 v[98:101], v[138:141], v[166:169], v[98:101]
	v_add_u32_e32 v138, s66, v241
	v_add3_u32 v171, v138, v239, v238
	v_add3_u32 v170, v138, v237, v238
	ds_read_b128 v[138:141], v171 offset:32768
	v_mfma_f32_16x16x32_bf16 v[86:89], v[154:157], v[162:165], v[86:89]
	v_mul_lo_u32 v162, s37, v235
	v_or_b32_e32 v174, v162, v236
	s_cselect_b32 s66, s76, s71
	v_mfma_f32_16x16x32_bf16 v[94:97], v[154:157], v[146:149], v[94:97]
	s_ashr_i32 s37, s36, 31
	s_add_i32 s80, s77, s80
	s_lshl_b64 s[36:37], s[36:37], 7
	v_mfma_f32_16x16x32_bf16 v[90:93], v[154:157], v[150:153], v[90:93]
	s_add_u32 s56, s79, s36
	s_addc_u32 s57, s78, s37
	v_lshlrev_b32_e32 v176, 1, v174
	v_mfma_f32_16x16x32_bf16 v[82:85], v[154:157], v[166:169], v[82:85]
	ds_read_b128 v[146:149], v170
	ds_read_b128 v[150:153], v170 offset:2048
	ds_read_b128 v[154:157], v171 offset:34816
	ds_read_b128 v[162:165], v170 offset:4096
	ds_read_b128 v[166:169], v170 offset:6144
	v_lshl_add_u64 v[174:175], s[56:57], 0, v[0:1]
	s_mov_b32 m0, s80
	s_waitcnt lgkmcnt(0)
	v_mfma_f32_16x16x32_bf16 v[158:161], v[138:141], v[146:149], v[158:161]
	v_mfma_f32_16x16x32_bf16 v[142:145], v[138:141], v[150:153], v[142:145]
	v_mfma_f32_16x16x32_bf16 v[134:137], v[138:141], v[162:165], v[134:137]
	v_mfma_f32_16x16x32_bf16 v[130:133], v[138:141], v[166:169], v[130:133]
	ds_read_b128 v[138:141], v171 offset:36864
	ds_read_b128 v[170:173], v171 offset:38912
	global_load_lds_dwordx4 v[174:175], off
	v_mfma_f32_16x16x32_bf16 v[126:129], v[154:157], v[146:149], v[126:129]
	s_add_i32 m0, s80, 0x2000
	v_mfma_f32_16x16x32_bf16 v[122:125], v[154:157], v[150:153], v[122:125]
	v_mfma_f32_16x16x32_bf16 v[118:121], v[154:157], v[162:165], v[118:121]
	v_mfma_f32_16x16x32_bf16 v[114:117], v[154:157], v[166:169], v[114:117]
	v_lshl_add_u64 v[154:155], v[174:175], 0, s[14:15]
	v_lshl_add_u64 v[156:157], v[174:175], 0, s[8:9]
	global_load_lds_dwordx4 v[154:155], off
	s_add_i32 m0, s80, 0x4000
	v_lshl_add_u64 v[174:175], v[174:175], 0, s[34:35]
	global_load_lds_dwordx4 v[156:157], off
	s_add_i32 m0, s80, 0x6000
	s_add_u32 s56, s81, s36
	global_load_lds_dwordx4 v[174:175], off
	s_addc_u32 s57, s66, s37
	s_add_i32 m0, s80, 0x8000
	s_waitcnt lgkmcnt(0)
	v_mfma_f32_16x16x32_bf16 v[110:113], v[138:141], v[146:149], v[110:113]
	global_load_lds_dwordx4 v176, s[56:57]
	s_add_u32 s56, s81, s82
	s_addc_u32 s57, s66, 0
	s_add_u32 s36, s56, s36
	s_addc_u32 s37, s57, s37
	s_add_i32 m0, s80, 0xa000
	v_mfma_f32_16x16x32_bf16 v[106:109], v[138:141], v[150:153], v[106:109]
	global_load_lds_dwordx4 v176, s[36:37]
	s_add_i32 s36, s20, 1
	s_cmp_lg_u32 s20, 2
	v_mfma_f32_16x16x32_bf16 v[102:105], v[138:141], v[162:165], v[102:105]
	s_cselect_b32 s20, s36, 0
	s_add_i32 s36, s23, 1
	s_cmp_lg_u32 s23, 2
	v_mfma_f32_16x16x32_bf16 v[98:101], v[138:141], v[166:169], v[98:101]
	s_cselect_b32 s23, s36, 0
	s_add_i32 s28, s28, 1
	s_cmp_eq_u32 s28, 4
	v_mfma_f32_16x16x32_bf16 v[94:97], v[170:173], v[146:149], v[94:97]
	v_mfma_f32_16x16x32_bf16 v[90:93], v[170:173], v[150:153], v[90:93]
	v_mfma_f32_16x16x32_bf16 v[86:89], v[170:173], v[162:165], v[86:89]
	v_mfma_f32_16x16x32_bf16 v[82:85], v[170:173], v[166:169], v[82:85]
	s_cbranch_scc0 .LBB0_471
	s_mov_b32 s66, s20
	s_mov_b32 s28, s23
	s_xor_b64 s[36:37], s[38:39], -1
	s_andn2_b64 vcc, exec, s[36:37]
	s_cbranch_vccz .LBB0_432
	s_branch .LBB0_433
